# combo10 + small_gemm epilogue operand loads issued before the K loop
# baseline (speedup 1.0000x reference)
;     __device__ __forceinline__ void operator()(int row, int col, const f32x4& acc) const {
;         if constexpr (NORM) { const f32x4 bv = *(const f32x4*)(base + (size_t)row * DM + col); const f32x4 v = acc + bv;
;             float ss = (v[0] * v[0] + v[1] * v[1]) + (v[2] * v[2] + v[3] * v[3]);
;             u32x2 w; w.x = cvt_pk_bf16(v[0], v[1]); w.y = cvt_pk_bf16(v[2], v[3]); *(u32x2*)(a3 + (size_t)row * DM + col) = w;
;             ss += __shfl_xor(ss, 16); ss += __shfl_xor(ss, 32); if ((threadIdx.x & 48) == 0) atomicAdd(rowss + row, ss);
; template <int KS, class Epi>
; __device__ __forceinline__ void small_gemm(const bf16_t* __restrict__ A, int lda, int a_grp_step, const bf16_t* __restrict__ Bt, int N, const Epi& E, LAS unsigned char* lds) {
;     ...
;     for (int pair = blockIdx.x; pair * 2 < ntile; pair += gridDim.x) {
;         const int tile = pair * 2 + th, tr = tile & 15, tc = tile >> 4, row0 = MP + tr * 32, col0 = tc * 32;
;         const bf16_t* ap = A + (size_t)(row0 + fr) * lda + (col0 >> 8) * a_grp_step + kq * (KS * 32) + 8 * fq;
;         const bf16_t* bp = Bt + (size_t)(col0 + fr) * K + kq * (KS * 32) + 8 * fq;
;         bf16x8 a[KS][2], b[KS][2];
; #pragma unroll
;         for (int k = 0; k < KS; ++k)
; #pragma unroll
;             for (int m = 0; m < 2; ++m) { a[k][m] = *(const bf16x8*)(ap + (size_t)(16 * m) * lda + 32 * k); b[k][m] = *(const bf16x8*)(bp + (size_t)(16 * m) * K + 32 * k); }
;         f32x4 acc[2][2];
; #pragma unroll
;         for (int mi = 0; mi < 2; ++mi)
; #pragma unroll
;             for (int ni = 0; ni < 2; ++ni) acc[mi][ni] = (f32x4){0.f, 0.f, 0.f, 0.f};
; #pragma unroll
;         for (int k = 0; k < KS; ++k)
; #pragma unroll
;             for (int mi = 0; mi < 2; ++mi)
; #pragma unroll
;                 for (int ni = 0; ni < 2; ++ni) acc[mi][ni] = mfma16(b[k][ni], a[k][mi], acc[mi][ni]);
; #pragma unroll
;         for (int mi = 0; mi < 2; ++mi)
; #pragma unroll
;             for (int ni = 0; ni < 2; ++ni) red[(wid * 4 + mi * 2 + ni) * 64 + lane] = acc[mi][ni];
;         lds_barrier();
;         {
;             const int sub = kq, mi = sub >> 1, ni = sub & 1;
;             f32x4 s = red[((th * 4 + 0) * 4 + sub) * 64 + lane];
; #pragma unroll
;             for (int q = 1; q < 4; ++q) s += red[((th * 4 + q) * 4 + sub) * 64 + lane];
;             E(row0 + 16 * mi + fr, col0 + 16 * ni + 4 * fq, s);
.LBB0_729:
	v_and_b32_e32 v70, 0xffffffe0, v9
	v_or_b32_e32 v18, v70, v146
	v_and_b32_e32 v0, 0x1e0, v10
	s_waitcnt lgkmcnt(0)
	v_ashrrev_i32_e32 v19, 31, v18
	v_or_b32_e32 v17, 0x4000, v0
	v_lshlrev_b64 v[18:19], 11, v[18:19]
	v_lshl_add_u64 v[62:63], v[4:5], 0, v[18:19]
	v_or_b32_e32 v0, v17, v146
	v_lshlrev_b32_e32 v0, 11, v0
	v_lshl_add_u64 v[64:65], v[2:3], 0, v[0:1]
	v_add_co_u32_e64 v66, s[2:3], s14, v64
	v_addc_co_u32_e64 v67, s[2:3], 0, v65, s[2:3]
	v_add_co_u32_e64 v68, s[2:3], s14, v62
	v_addc_co_u32_e64 v69, s[2:3], 0, v63, s[2:3]
	v_or_b32_e32 v17, v7, v17
	v_lshlrev_b32_e32 v0, 12, v17
	v_cmp_lt_i32_e64 s[2:3], v14, v15
	v_or_b32_e32 v38, v70, v8
	v_ashrrev_i32_e32 v39, 31, v38
	v_lshl_add_u64 v[144:145], s[4:5], 0, v[0:1]
	v_lshl_add_u64 v[144:145], v[38:39], 2, v[144:145]
	global_load_dwordx4 v[140:143], v[144:145], off
	global_load_dwordx4 v[158:161], v[62:63], off
	global_load_dwordx4 v[162:165], v[64:65], off
	global_load_dwordx4 v[166:169], v[66:67], off
	global_load_dwordx4 v[170:173], v[68:69], off
	global_load_dwordx4 v[174:177], v[62:63], off offset:64
	global_load_dwordx4 v[178:181], v[64:65], off offset:64
	global_load_dwordx4 v[186:189], v[66:67], off offset:64
	global_load_dwordx4 v[190:193], v[68:69], off offset:64
	global_load_dwordx4 v[194:197], v[62:63], off offset:128
	global_load_dwordx4 v[198:201], v[64:65], off offset:128
	global_load_dwordx4 v[202:205], v[66:67], off offset:128
	global_load_dwordx4 v[206:209], v[68:69], off offset:128
	global_load_dwordx4 v[210:213], v[62:63], off offset:192
	global_load_dwordx4 v[214:217], v[64:65], off offset:192
	global_load_dwordx4 v[218:221], v[66:67], off offset:192
	global_load_dwordx4 v[222:225], v[68:69], off offset:192
	global_load_dwordx4 v[226:229], v[62:63], off offset:256
	global_load_dwordx4 v[230:233], v[64:65], off offset:256
	global_load_dwordx4 v[234:237], v[66:67], off offset:256
	global_load_dwordx4 v[238:241], v[68:69], off offset:256
	global_load_dwordx4 v[242:245], v[62:63], off offset:320
	global_load_dwordx4 v[118:121], v[64:65], off offset:320
	global_load_dwordx4 v[122:125], v[66:67], off offset:320
	global_load_dwordx4 v[148:151], v[68:69], off offset:320
	s_waitcnt vmcnt(20)
	v_mfma_f32_16x16x32_bf16 v[18:21], v[158:161], v[162:165], 0
	v_mfma_f32_16x16x32_bf16 v[22:25], v[158:161], v[166:169], 0
	v_mfma_f32_16x16x32_bf16 v[26:29], v[170:173], v[162:165], 0
	v_mfma_f32_16x16x32_bf16 v[30:33], v[170:173], v[166:169], 0
	global_load_dwordx4 v[158:161], v[62:63], off offset:384
	global_load_dwordx4 v[162:165], v[64:65], off offset:384
	global_load_dwordx4 v[166:169], v[66:67], off offset:384
	global_load_dwordx4 v[170:173], v[68:69], off offset:384
	s_waitcnt vmcnt(20)
	v_mfma_f32_16x16x32_bf16 v[18:21], v[174:177], v[178:181], v[18:21]
	v_mfma_f32_16x16x32_bf16 v[22:25], v[174:177], v[186:189], v[22:25]
	v_mfma_f32_16x16x32_bf16 v[26:29], v[190:193], v[178:181], v[26:29]
	v_mfma_f32_16x16x32_bf16 v[30:33], v[190:193], v[186:189], v[30:33]
	global_load_dwordx4 v[174:177], v[62:63], off offset:448
	global_load_dwordx4 v[178:181], v[64:65], off offset:448
	global_load_dwordx4 v[186:189], v[66:67], off offset:448
	global_load_dwordx4 v[190:193], v[68:69], off offset:448
	s_waitcnt vmcnt(20)
	v_mfma_f32_16x16x32_bf16 v[18:21], v[194:197], v[198:201], v[18:21]
	v_mfma_f32_16x16x32_bf16 v[22:25], v[194:197], v[202:205], v[22:25]
	v_mfma_f32_16x16x32_bf16 v[26:29], v[206:209], v[198:201], v[26:29]
	v_mfma_f32_16x16x32_bf16 v[30:33], v[206:209], v[202:205], v[30:33]
	s_waitcnt vmcnt(16)
	v_mfma_f32_16x16x32_bf16 v[18:21], v[210:213], v[214:217], v[18:21]
	v_mfma_f32_16x16x32_bf16 v[22:25], v[210:213], v[218:221], v[22:25]
	v_mfma_f32_16x16x32_bf16 v[26:29], v[222:225], v[214:217], v[26:29]
	v_mfma_f32_16x16x32_bf16 v[30:33], v[222:225], v[218:221], v[30:33]
	s_waitcnt vmcnt(12)
	v_mfma_f32_16x16x32_bf16 v[18:21], v[226:229], v[230:233], v[18:21]
	v_mfma_f32_16x16x32_bf16 v[22:25], v[226:229], v[234:237], v[22:25]
	v_mfma_f32_16x16x32_bf16 v[26:29], v[238:241], v[230:233], v[26:29]
	v_mfma_f32_16x16x32_bf16 v[30:33], v[238:241], v[234:237], v[30:33]
	s_waitcnt vmcnt(8)
	v_mfma_f32_16x16x32_bf16 v[18:21], v[242:245], v[118:121], v[18:21]
	v_mfma_f32_16x16x32_bf16 v[22:25], v[242:245], v[122:125], v[22:25]
	v_mfma_f32_16x16x32_bf16 v[26:29], v[148:151], v[118:121], v[26:29]
	v_mfma_f32_16x16x32_bf16 v[30:33], v[148:151], v[122:125], v[30:33]
	s_waitcnt vmcnt(4)
	v_mfma_f32_16x16x32_bf16 v[18:21], v[158:161], v[162:165], v[18:21]
	v_mfma_f32_16x16x32_bf16 v[22:25], v[158:161], v[166:169], v[22:25]
	v_mfma_f32_16x16x32_bf16 v[26:29], v[170:173], v[162:165], v[26:29]
	v_mfma_f32_16x16x32_bf16 v[30:33], v[170:173], v[166:169], v[30:33]
	s_waitcnt vmcnt(0)
	v_mfma_f32_16x16x32_bf16 v[18:21], v[174:177], v[178:181], v[18:21]
	v_mfma_f32_16x16x32_bf16 v[22:25], v[174:177], v[186:189], v[22:25]
	v_mfma_f32_16x16x32_bf16 v[26:29], v[190:193], v[178:181], v[26:29]
	v_mfma_f32_16x16x32_bf16 v[30:33], v[190:193], v[186:189], v[30:33]
	s_nop 7
	s_nop 3
	ds_write_b128 v11, v[18:21]
	ds_write_b128 v11, v[26:29] offset:1024
	ds_write_b128 v11, v[22:25] offset:2048
	ds_write_b128 v11, v[30:33] offset:3072
	v_lshl_add_u64 v[18:19], s[4:5], 0, v[0:1]
	s_waitcnt lgkmcnt(0)
	s_barrier
	v_lshl_add_u64 v[18:19], v[38:39], 2, v[18:19]
	ds_read_b128 v[22:25], v6
	ds_read_b128 v[26:29], v12 offset:4096
	ds_read_b128 v[30:33], v12 offset:8192
	ds_read_b128 v[34:37], v12 offset:12288
	v_cndmask_b32_e64 v0, v13, v14, s[2:3]
	v_lshlrev_b32_e32 v0, 2, v0
	s_waitcnt lgkmcnt(0)
	v_pk_add_f32 v[24:25], v[24:25], v[28:29]
	v_pk_add_f32 v[22:23], v[22:23], v[26:27]
	v_pk_add_f32 v[24:25], v[24:25], v[32:33]
	v_pk_add_f32 v[22:23], v[22:23], v[30:31]
	v_pk_add_f32 v[24:25], v[24:25], v[36:37]
	v_pk_add_f32 v[22:23], v[22:23], v[34:35]
	v_cmp_lt_i32_e64 s[2:3], v16, v15
	s_waitcnt vmcnt(0)
	v_pk_add_f32 v[20:21], v[24:25], v[142:143]
	v_pk_add_f32 v[18:19], v[22:23], v[140:141]
	v_mul_f32_e32 v23, v21, v21
	v_mul_f32_e32 v22, v19, v19
	v_fmac_f32_e32 v22, v18, v18
	v_fmac_f32_e32 v23, v20, v20
	v_add_f32_e32 v24, v22, v23
	ds_bpermute_b32 v0, v0, v24
	v_cndmask_b32_e64 v25, v13, v16, s[2:3]
	v_cvt_pk_bf16_f32 v22, v18, v19
	v_cvt_pk_bf16_f32 v23, v20, v21
	s_waitcnt lgkmcnt(0)
	v_add_f32_e32 v18, v24, v0
	v_lshlrev_b32_e32 v0, 2, v25
	ds_bpermute_b32 v19, v0, v18
	v_lshlrev_b32_e32 v0, 11, v17
	v_lshl_add_u64 v[20:21], s[6:7], 0, v[0:1]
	v_lshl_add_u64 v[20:21], v[38:39], 1, v[20:21]
	global_store_dwordx2 v[20:21], v[22:23], off
	s_and_saveexec_b64 s[0:1], vcc
	s_cbranch_execz .LBB0_728
	v_lshlrev_b32_e32 v0, 2, v17
	s_waitcnt lgkmcnt(0)
	v_add_f32_e32 v17, v18, v19
	global_atomic_add_f32 v0, v17, s[10:11]
	s_branch .LBB0_728

;     __device__ __forceinline__ void operator()(int row, int col, const f32x4& acc) const {
;         if constexpr (NORM) { const f32x4 bv = *(const f32x4*)(base + (size_t)row * DM + col); const f32x4 v = acc + bv;
;             float ss = (v[0] * v[0] + v[1] * v[1]) + (v[2] * v[2] + v[3] * v[3]);
;             u32x2 w; w.x = cvt_pk_bf16(v[0], v[1]); w.y = cvt_pk_bf16(v[2], v[3]); *(u32x2*)(a3 + (size_t)row * DM + col) = w;
;             ss += __shfl_xor(ss, 16); ss += __shfl_xor(ss, 32); if ((threadIdx.x & 48) == 0) atomicAdd(rowss + row, ss);
; template <int KS, class Epi>
; __device__ __forceinline__ void small_gemm(const bf16_t* __restrict__ A, int lda, int a_grp_step, const bf16_t* __restrict__ Bt, int N, const Epi& E, LAS unsigned char* lds) {
;     ...
;     for (int pair = blockIdx.x; pair * 2 < ntile; pair += gridDim.x) {
;         const int tile = pair * 2 + th, tr = tile & 15, tc = tile >> 4, row0 = MP + tr * 32, col0 = tc * 32;
;         const bf16_t* ap = A + (size_t)(row0 + fr) * lda + (col0 >> 8) * a_grp_step + kq * (KS * 32) + 8 * fq;
;         const bf16_t* bp = Bt + (size_t)(col0 + fr) * K + kq * (KS * 32) + 8 * fq;
;         bf16x8 a[KS][2], b[KS][2];
; #pragma unroll
;         for (int k = 0; k < KS; ++k)
; #pragma unroll
;             for (int m = 0; m < 2; ++m) { a[k][m] = *(const bf16x8*)(ap + (size_t)(16 * m) * lda + 32 * k); b[k][m] = *(const bf16x8*)(bp + (size_t)(16 * m) * K + 32 * k); }
;         f32x4 acc[2][2];
; #pragma unroll
;         for (int mi = 0; mi < 2; ++mi)
; #pragma unroll
;             for (int ni = 0; ni < 2; ++ni) acc[mi][ni] = (f32x4){0.f, 0.f, 0.f, 0.f};
; #pragma unroll
;         for (int k = 0; k < KS; ++k)
; #pragma unroll
;             for (int mi = 0; mi < 2; ++mi)
; #pragma unroll
;                 for (int ni = 0; ni < 2; ++ni) acc[mi][ni] = mfma16(b[k][ni], a[k][mi], acc[mi][ni]);
; #pragma unroll
;         for (int mi = 0; mi < 2; ++mi)
; #pragma unroll
;             for (int ni = 0; ni < 2; ++ni) red[(wid * 4 + mi * 2 + ni) * 64 + lane] = acc[mi][ni];
;         lds_barrier();
;         {
;             const int sub = kq, mi = sub >> 1, ni = sub & 1;
;             f32x4 s = red[((th * 4 + 0) * 4 + sub) * 64 + lane];
; #pragma unroll
;             for (int q = 1; q < 4; ++q) s += red[((th * 4 + q) * 4 + sub) * 64 + lane];
;             E(row0 + 16 * mi + fr, col0 + 16 * ni + 4 * fq, s);
.LBB0_776:
	v_and_b32_e32 v70, 0xffffffe0, v9
	s_waitcnt lgkmcnt(0)
	v_or_b32_e32 v18, v70, v146
	v_and_b32_e32 v0, 0x1e0, v10
	v_ashrrev_i32_e32 v19, 31, v18
	v_or_b32_e32 v17, 0x4000, v0
	v_lshlrev_b64 v[18:19], 11, v[18:19]
	v_lshl_add_u64 v[62:63], v[4:5], 0, v[18:19]
	v_or_b32_e32 v0, v17, v146
	v_lshlrev_b32_e32 v0, 11, v0
	v_lshl_add_u64 v[64:65], v[2:3], 0, v[0:1]
	v_add_co_u32_e64 v66, s[2:3], s8, v64
	v_addc_co_u32_e64 v67, s[2:3], 0, v65, s[2:3]
	v_add_co_u32_e64 v68, s[2:3], s8, v62
	v_addc_co_u32_e64 v69, s[2:3], 0, v63, s[2:3]
	v_or_b32_e32 v0, v7, v17
	v_cmp_lt_i32_e64 s[2:3], v14, v15
	v_cndmask_b32_e64 v17, v13, v14, s[2:3]
	v_lshlrev_b32_e32 v17, 2, v17
	v_cmp_lt_i32_e64 s[2:3], v16, v15
	v_or_b32_e32 v38, v70, v8
	v_ashrrev_i32_e32 v39, 31, v38
	v_lshlrev_b64 v[144:145], 12, v[0:1]
	v_lshl_add_u64 v[144:145], s[4:5], 0, v[144:145]
	v_lshl_add_u64 v[144:145], v[38:39], 2, v[144:145]
	global_load_dwordx4 v[140:143], v[144:145], off
	global_load_dwordx4 v[158:161], v[62:63], off
	global_load_dwordx4 v[162:165], v[64:65], off
	global_load_dwordx4 v[166:169], v[66:67], off
	global_load_dwordx4 v[170:173], v[68:69], off
	global_load_dwordx4 v[174:177], v[62:63], off offset:64
	global_load_dwordx4 v[178:181], v[64:65], off offset:64
	global_load_dwordx4 v[186:189], v[66:67], off offset:64
	global_load_dwordx4 v[190:193], v[68:69], off offset:64
	global_load_dwordx4 v[194:197], v[62:63], off offset:128
	global_load_dwordx4 v[198:201], v[64:65], off offset:128
	global_load_dwordx4 v[202:205], v[66:67], off offset:128
	global_load_dwordx4 v[206:209], v[68:69], off offset:128
	global_load_dwordx4 v[210:213], v[62:63], off offset:192
	global_load_dwordx4 v[214:217], v[64:65], off offset:192
	global_load_dwordx4 v[218:221], v[66:67], off offset:192
	global_load_dwordx4 v[222:225], v[68:69], off offset:192
	global_load_dwordx4 v[226:229], v[62:63], off offset:256
	global_load_dwordx4 v[230:233], v[64:65], off offset:256
	global_load_dwordx4 v[234:237], v[66:67], off offset:256
	global_load_dwordx4 v[238:241], v[68:69], off offset:256
	global_load_dwordx4 v[242:245], v[62:63], off offset:320
	global_load_dwordx4 v[118:121], v[64:65], off offset:320
	global_load_dwordx4 v[122:125], v[66:67], off offset:320
	global_load_dwordx4 v[148:151], v[68:69], off offset:320
	s_waitcnt vmcnt(20)
	v_mfma_f32_16x16x32_bf16 v[18:21], v[158:161], v[162:165], 0
	v_mfma_f32_16x16x32_bf16 v[22:25], v[158:161], v[166:169], 0
	v_mfma_f32_16x16x32_bf16 v[26:29], v[170:173], v[162:165], 0
	v_mfma_f32_16x16x32_bf16 v[30:33], v[170:173], v[166:169], 0
	global_load_dwordx4 v[158:161], v[62:63], off offset:384
	global_load_dwordx4 v[162:165], v[64:65], off offset:384
	global_load_dwordx4 v[166:169], v[66:67], off offset:384
	global_load_dwordx4 v[170:173], v[68:69], off offset:384
	s_waitcnt vmcnt(20)
	v_mfma_f32_16x16x32_bf16 v[18:21], v[174:177], v[178:181], v[18:21]
	v_mfma_f32_16x16x32_bf16 v[22:25], v[174:177], v[186:189], v[22:25]
	v_mfma_f32_16x16x32_bf16 v[26:29], v[190:193], v[178:181], v[26:29]
	v_mfma_f32_16x16x32_bf16 v[30:33], v[190:193], v[186:189], v[30:33]
	global_load_dwordx4 v[174:177], v[62:63], off offset:448
	global_load_dwordx4 v[178:181], v[64:65], off offset:448
	global_load_dwordx4 v[186:189], v[66:67], off offset:448
	global_load_dwordx4 v[190:193], v[68:69], off offset:448
	s_waitcnt vmcnt(20)
	v_mfma_f32_16x16x32_bf16 v[18:21], v[194:197], v[198:201], v[18:21]
	v_mfma_f32_16x16x32_bf16 v[22:25], v[194:197], v[202:205], v[22:25]
	v_mfma_f32_16x16x32_bf16 v[26:29], v[206:209], v[198:201], v[26:29]
	v_mfma_f32_16x16x32_bf16 v[30:33], v[206:209], v[202:205], v[30:33]
	s_waitcnt vmcnt(16)
	v_mfma_f32_16x16x32_bf16 v[18:21], v[210:213], v[214:217], v[18:21]
	v_mfma_f32_16x16x32_bf16 v[22:25], v[210:213], v[218:221], v[22:25]
	v_mfma_f32_16x16x32_bf16 v[26:29], v[222:225], v[214:217], v[26:29]
	v_mfma_f32_16x16x32_bf16 v[30:33], v[222:225], v[218:221], v[30:33]
	s_waitcnt vmcnt(12)
	v_mfma_f32_16x16x32_bf16 v[18:21], v[226:229], v[230:233], v[18:21]
	v_mfma_f32_16x16x32_bf16 v[22:25], v[226:229], v[234:237], v[22:25]
	v_mfma_f32_16x16x32_bf16 v[26:29], v[238:241], v[230:233], v[26:29]
	v_mfma_f32_16x16x32_bf16 v[30:33], v[238:241], v[234:237], v[30:33]
	s_waitcnt vmcnt(8)
	v_mfma_f32_16x16x32_bf16 v[18:21], v[242:245], v[118:121], v[18:21]
	v_mfma_f32_16x16x32_bf16 v[22:25], v[242:245], v[122:125], v[22:25]
	v_mfma_f32_16x16x32_bf16 v[26:29], v[148:151], v[118:121], v[26:29]
	v_mfma_f32_16x16x32_bf16 v[30:33], v[148:151], v[122:125], v[30:33]
	s_waitcnt vmcnt(4)
	v_mfma_f32_16x16x32_bf16 v[18:21], v[158:161], v[162:165], v[18:21]
	v_mfma_f32_16x16x32_bf16 v[22:25], v[158:161], v[166:169], v[22:25]
	v_mfma_f32_16x16x32_bf16 v[26:29], v[170:173], v[162:165], v[26:29]
	v_mfma_f32_16x16x32_bf16 v[30:33], v[170:173], v[166:169], v[30:33]
	s_waitcnt vmcnt(0)
	v_mfma_f32_16x16x32_bf16 v[18:21], v[174:177], v[178:181], v[18:21]
	v_mfma_f32_16x16x32_bf16 v[22:25], v[174:177], v[186:189], v[22:25]
	v_mfma_f32_16x16x32_bf16 v[26:29], v[190:193], v[178:181], v[26:29]
	v_mfma_f32_16x16x32_bf16 v[30:33], v[190:193], v[186:189], v[30:33]
	s_nop 7
	s_nop 3
	ds_write_b128 v11, v[18:21]
	ds_write_b128 v11, v[26:29] offset:1024
	ds_write_b128 v11, v[22:25] offset:2048
	ds_write_b128 v11, v[30:33] offset:3072
	v_lshlrev_b64 v[18:19], 12, v[0:1]
	v_lshl_add_u64 v[18:19], s[4:5], 0, v[18:19]
	s_waitcnt lgkmcnt(0)
	s_barrier
	v_lshl_add_u64 v[18:19], v[38:39], 2, v[18:19]
	ds_read_b128 v[22:25], v6
	ds_read_b128 v[26:29], v12 offset:4096
	ds_read_b128 v[30:33], v12 offset:8192
	ds_read_b128 v[34:37], v12 offset:12288
	s_waitcnt lgkmcnt(2)
	v_pk_add_f32 v[24:25], v[24:25], v[28:29]
	v_pk_add_f32 v[22:23], v[22:23], v[26:27]
	s_waitcnt lgkmcnt(1)
	v_pk_add_f32 v[24:25], v[24:25], v[32:33]
	v_pk_add_f32 v[22:23], v[22:23], v[30:31]
	s_waitcnt lgkmcnt(0)
	v_pk_add_f32 v[24:25], v[24:25], v[36:37]
	v_pk_add_f32 v[22:23], v[22:23], v[34:35]
	s_waitcnt vmcnt(0)
	v_pk_add_f32 v[20:21], v[24:25], v[142:143]
	v_pk_add_f32 v[18:19], v[22:23], v[140:141]
	v_mul_f32_e32 v23, v21, v21
	v_mul_f32_e32 v22, v19, v19
	v_fmac_f32_e32 v22, v18, v18
	v_fmac_f32_e32 v23, v20, v20
	v_add_f32_e32 v24, v22, v23
	ds_bpermute_b32 v17, v17, v24
	v_cndmask_b32_e64 v25, v13, v16, s[2:3]
	v_cvt_pk_bf16_f32 v22, v18, v19
	v_lshlrev_b32_e32 v18, 2, v25
	v_cvt_pk_bf16_f32 v23, v20, v21
	s_waitcnt lgkmcnt(0)
	v_add_f32_e32 v17, v24, v17
	ds_bpermute_b32 v18, v18, v17
	v_lshlrev_b64 v[20:21], 11, v[0:1]
	v_lshl_add_u64 v[20:21], s[10:11], 0, v[20:21]
	v_lshl_add_u64 v[20:21], v[38:39], 1, v[20:21]
	global_store_dwordx2 v[20:21], v[22:23], off
	s_and_saveexec_b64 s[0:1], vcc
	s_cbranch_execz .LBB0_775
	v_lshl_add_u64 v[20:21], v[0:1], 2, s[12:13]
	s_waitcnt lgkmcnt(0)
	v_add_f32_e32 v0, v17, v18
	global_atomic_add_f32 v[20:21], v0, off
	s_branch .LBB0_775

;     __device__ __forceinline__ void operator()(int row, int col, const f32x4& acc) const {
;         const f32x4 v = acc * rsqrtf(rowss[row] * (1.0f / 1024.0f) + 1e-6f);
;         if (col < 1024) { u32x2 w; w.x = cvt_pk_bf16(v[0], v[1]); w.y = cvt_pk_bf16(v[2], v[3]); *(u32x2*)(U + (size_t)row * DM + col) = w; }
;         else { u32x2 w; w.x = cvt_pk_bf16(silu_f(v[0]), silu_f(v[1])); w.y = cvt_pk_bf16(silu_f(v[2]), silu_f(v[3])); *(u32x2*)(SG + (size_t)row * DM + col - 1024) = w; } }
; template <int KS, class Epi>
; __device__ __forceinline__ void small_gemm(const bf16_t* __restrict__ A, int lda, int a_grp_step, const bf16_t* __restrict__ Bt, int N, const Epi& E, LAS unsigned char* lds) {
;     ...
;     for (int pair = blockIdx.x; pair * 2 < ntile; pair += gridDim.x) {
;         const int tile = pair * 2 + th, tr = tile & 15, tc = tile >> 4, row0 = MP + tr * 32, col0 = tc * 32;
;         const bf16_t* ap = A + (size_t)(row0 + fr) * lda + (col0 >> 8) * a_grp_step + kq * (KS * 32) + 8 * fq;
;         const bf16_t* bp = Bt + (size_t)(col0 + fr) * K + kq * (KS * 32) + 8 * fq;
;         bf16x8 a[KS][2], b[KS][2];
; #pragma unroll
;         for (int k = 0; k < KS; ++k)
; #pragma unroll
;             for (int m = 0; m < 2; ++m) { a[k][m] = *(const bf16x8*)(ap + (size_t)(16 * m) * lda + 32 * k); b[k][m] = *(const bf16x8*)(bp + (size_t)(16 * m) * K + 32 * k); }
;         f32x4 acc[2][2];
; #pragma unroll
;         for (int mi = 0; mi < 2; ++mi)
; #pragma unroll
;             for (int ni = 0; ni < 2; ++ni) acc[mi][ni] = (f32x4){0.f, 0.f, 0.f, 0.f};
; #pragma unroll
;         for (int k = 0; k < KS; ++k)
; #pragma unroll
;             for (int mi = 0; mi < 2; ++mi)
; #pragma unroll
;                 for (int ni = 0; ni < 2; ++ni) acc[mi][ni] = mfma16(b[k][ni], a[k][mi], acc[mi][ni]);
; #pragma unroll
;         for (int mi = 0; mi < 2; ++mi)
; #pragma unroll
;             for (int ni = 0; ni < 2; ++ni) red[(wid * 4 + mi * 2 + ni) * 64 + lane] = acc[mi][ni];
;         lds_barrier();
;         {
;             const int sub = kq, mi = sub >> 1, ni = sub & 1;
;             f32x4 s = red[((th * 4 + 0) * 4 + sub) * 64 + lane];
; #pragma unroll
;             for (int q = 1; q < 4; ++q) s += red[((th * 4 + q) * 4 + sub) * 64 + lane];
;             E(row0 + 16 * mi + fr, col0 + 16 * ni + 4 * fq, s);
.LBB0_837:
	v_and_b32_e32 v67, 0xffffffe0, v15
	v_or_b32_e32 v6, v67, v157
	v_and_b32_e32 v0, 0x1e0, v16
	v_ashrrev_i32_e32 v7, 31, v6
	v_or_b32_e32 v66, 0x4000, v0
	v_lshlrev_b64 v[6:7], 11, v[6:7]
	v_lshl_add_u64 v[10:11], v[4:5], 0, v[6:7]
	v_or_b32_e32 v0, v66, v157
	v_lshlrev_b32_e32 v0, 11, v0
	v_lshl_add_u64 v[60:61], v[2:3], 0, v[0:1]
	v_add_co_u32_e32 v62, vcc, s14, v60
	v_addc_co_u32_e32 v63, vcc, 0, v61, vcc
	v_add_co_u32_e32 v64, vcc, s14, v10
	v_addc_co_u32_e32 v65, vcc, 0, v11, vcc
	v_or_b32_e32 v144, v13, v66
	v_lshlrev_b32_e32 v144, 2, v144
	global_load_dword v140, v144, s[6:7]
	global_load_dwordx4 v[158:161], v[10:11], off
	global_load_dwordx4 v[162:165], v[60:61], off
	global_load_dwordx4 v[166:169], v[62:63], off
	global_load_dwordx4 v[170:173], v[64:65], off
	global_load_dwordx4 v[174:177], v[10:11], off offset:64
	global_load_dwordx4 v[178:181], v[60:61], off offset:64
	global_load_dwordx4 v[186:189], v[62:63], off offset:64
	global_load_dwordx4 v[190:193], v[64:65], off offset:64
	global_load_dwordx4 v[194:197], v[10:11], off offset:128
	global_load_dwordx4 v[198:201], v[60:61], off offset:128
	global_load_dwordx4 v[202:205], v[62:63], off offset:128
	global_load_dwordx4 v[206:209], v[64:65], off offset:128
	global_load_dwordx4 v[210:213], v[10:11], off offset:192
	global_load_dwordx4 v[214:217], v[60:61], off offset:192
	global_load_dwordx4 v[218:221], v[62:63], off offset:192
	global_load_dwordx4 v[222:225], v[64:65], off offset:192
	global_load_dwordx4 v[226:229], v[10:11], off offset:256
	global_load_dwordx4 v[230:233], v[60:61], off offset:256
	global_load_dwordx4 v[234:237], v[62:63], off offset:256
	global_load_dwordx4 v[238:241], v[64:65], off offset:256
	global_load_dwordx4 v[242:245], v[10:11], off offset:320
	global_load_dwordx4 v[118:121], v[60:61], off offset:320
	global_load_dwordx4 v[122:125], v[62:63], off offset:320
	global_load_dwordx4 v[148:151], v[64:65], off offset:320
	s_waitcnt vmcnt(20)
	v_mfma_f32_16x16x32_bf16 v[6:9], v[158:161], v[162:165], 0
	v_mfma_f32_16x16x32_bf16 v[22:25], v[158:161], v[166:169], 0
	v_mfma_f32_16x16x32_bf16 v[26:29], v[170:173], v[162:165], 0
	v_mfma_f32_16x16x32_bf16 v[30:33], v[170:173], v[166:169], 0
	global_load_dwordx4 v[158:161], v[10:11], off offset:384
	global_load_dwordx4 v[162:165], v[60:61], off offset:384
	global_load_dwordx4 v[166:169], v[62:63], off offset:384
	global_load_dwordx4 v[170:173], v[64:65], off offset:384
	s_waitcnt vmcnt(20)
	v_mfma_f32_16x16x32_bf16 v[6:9], v[174:177], v[178:181], v[6:9]
	v_mfma_f32_16x16x32_bf16 v[22:25], v[174:177], v[186:189], v[22:25]
	v_mfma_f32_16x16x32_bf16 v[26:29], v[190:193], v[178:181], v[26:29]
	v_mfma_f32_16x16x32_bf16 v[30:33], v[190:193], v[186:189], v[30:33]
	global_load_dwordx4 v[174:177], v[10:11], off offset:448
	global_load_dwordx4 v[178:181], v[60:61], off offset:448
	global_load_dwordx4 v[186:189], v[62:63], off offset:448
	global_load_dwordx4 v[190:193], v[64:65], off offset:448
	s_waitcnt vmcnt(20)
	v_mfma_f32_16x16x32_bf16 v[6:9], v[194:197], v[198:201], v[6:9]
	v_mfma_f32_16x16x32_bf16 v[22:25], v[194:197], v[202:205], v[22:25]
	v_mfma_f32_16x16x32_bf16 v[26:29], v[206:209], v[198:201], v[26:29]
	v_mfma_f32_16x16x32_bf16 v[30:33], v[206:209], v[202:205], v[30:33]
	s_waitcnt vmcnt(16)
	v_mfma_f32_16x16x32_bf16 v[6:9], v[210:213], v[214:217], v[6:9]
	v_mfma_f32_16x16x32_bf16 v[22:25], v[210:213], v[218:221], v[22:25]
	v_mfma_f32_16x16x32_bf16 v[26:29], v[222:225], v[214:217], v[26:29]
	v_mfma_f32_16x16x32_bf16 v[30:33], v[222:225], v[218:221], v[30:33]
	s_waitcnt vmcnt(12)
	v_mfma_f32_16x16x32_bf16 v[6:9], v[226:229], v[230:233], v[6:9]
	v_mfma_f32_16x16x32_bf16 v[22:25], v[226:229], v[234:237], v[22:25]
	v_mfma_f32_16x16x32_bf16 v[26:29], v[238:241], v[230:233], v[26:29]
	v_mfma_f32_16x16x32_bf16 v[30:33], v[238:241], v[234:237], v[30:33]
	s_waitcnt vmcnt(8)
	v_mfma_f32_16x16x32_bf16 v[6:9], v[242:245], v[118:121], v[6:9]
	v_mfma_f32_16x16x32_bf16 v[22:25], v[242:245], v[122:125], v[22:25]
	v_mfma_f32_16x16x32_bf16 v[26:29], v[148:151], v[118:121], v[26:29]
	v_mfma_f32_16x16x32_bf16 v[30:33], v[148:151], v[122:125], v[30:33]
	s_waitcnt vmcnt(4)
	v_mfma_f32_16x16x32_bf16 v[6:9], v[158:161], v[162:165], v[6:9]
	v_mfma_f32_16x16x32_bf16 v[22:25], v[158:161], v[166:169], v[22:25]
	v_mfma_f32_16x16x32_bf16 v[26:29], v[170:173], v[162:165], v[26:29]
	v_mfma_f32_16x16x32_bf16 v[30:33], v[170:173], v[166:169], v[30:33]
	s_waitcnt vmcnt(0)
	v_mfma_f32_16x16x32_bf16 v[6:9], v[174:177], v[178:181], v[6:9]
	v_mfma_f32_16x16x32_bf16 v[22:25], v[174:177], v[186:189], v[22:25]
	v_mfma_f32_16x16x32_bf16 v[26:29], v[190:193], v[178:181], v[26:29]
	v_mfma_f32_16x16x32_bf16 v[30:33], v[190:193], v[186:189], v[30:33]
	s_nop 7
	s_nop 3
	ds_write_b128 v17, v[6:9]
	ds_write_b128 v17, v[26:29] offset:1024
	ds_write_b128 v17, v[22:25] offset:2048
	ds_write_b128 v17, v[30:33] offset:3072
	v_or_b32_e32 v7, v13, v66
	s_waitcnt lgkmcnt(0)
	s_barrier
	v_lshlrev_b32_e32 v0, 2, v7
	ds_read_b128 v[8:11], v12
	ds_read_b128 v[20:23], v18 offset:4096
	ds_read_b128 v[24:27], v18 offset:8192
	ds_read_b128 v[28:31], v18 offset:12288
	v_or_b32_e32 v6, v67, v14
	v_cmp_lt_i32_e32 vcc, s16, v6
	s_waitcnt lgkmcnt(2)
	v_pk_add_f32 v[8:9], v[8:9], v[20:21]
	v_pk_add_f32 v[10:11], v[10:11], v[22:23]
	s_waitcnt lgkmcnt(1)
	v_pk_add_f32 v[8:9], v[8:9], v[24:25]
	v_pk_add_f32 v[10:11], v[10:11], v[26:27]
	s_waitcnt vmcnt(0)
	v_fmamk_f32 v0, v140, 0x3a800000, v19
	v_mul_f32_e32 v20, 0x4b800000, v0
	v_cmp_gt_f32_e64 s[2:3], s15, v0
	s_waitcnt lgkmcnt(0)
	v_pk_add_f32 v[10:11], v[10:11], v[30:31]
	v_cndmask_b32_e64 v0, v0, v20, s[2:3]
	v_rsq_f32_e32 v0, v0
	v_pk_add_f32 v[20:21], v[8:9], v[28:29]
	v_mul_f32_e32 v8, 0x45800000, v0
	v_cndmask_b32_e64 v0, v0, v8, s[2:3]
	v_pk_mul_f32 v[8:9], v[10:11], v[0:1] op_sel_hi:[1,0]
	v_pk_mul_f32 v[10:11], v[20:21], v[0:1] op_sel_hi:[1,0]
	v_lshlrev_b32_e32 v0, 11, v7
	s_and_saveexec_b64 s[0:1], vcc
	s_xor_b64 s[2:3], exec, s[0:1]
	s_cbranch_execz .LBB0_839
	v_mul_f32_e32 v7, 0xbfb8aa3b, v10
	v_exp_f32_e32 v7, v7
	v_mul_f32_e32 v20, 0xbfb8aa3b, v11
	v_exp_f32_e32 v20, v20
	v_mul_f32_e32 v22, 0xbfb8aa3b, v9
	v_add_f32_e32 v7, 1.0, v7
	v_exp_f32_e32 v23, v22
	v_add_f32_e32 v21, 1.0, v20
	v_rcp_f32_e32 v20, v7
	v_mul_f32_e32 v7, 0xbfb8aa3b, v8
	v_exp_f32_e32 v7, v7
	v_rcp_f32_e32 v21, v21
	v_add_f32_e32 v7, 1.0, v7
	v_rcp_f32_e32 v22, v7
	v_add_f32_e32 v7, 1.0, v23
	v_rcp_f32_e32 v23, v7
	v_pk_mul_f32 v[10:11], v[10:11], v[20:21]
	v_mov_b32_e32 v7, v1
	v_cvt_pk_bf16_f32 v10, v10, v11
	v_pk_mul_f32 v[8:9], v[8:9], v[22:23]
	s_nop 0
	v_cvt_pk_bf16_f32 v11, v8, v9
	v_lshl_add_u64 v[8:9], s[50:51], 0, v[0:1]
	v_lshl_add_u64 v[6:7], v[6:7], 1, v[8:9]
	v_add_co_u32_e32 v6, vcc, 0x71ff000, v6
	s_nop 1
	v_addc_co_u32_e32 v7, vcc, 0, v7, vcc
	global_store_dwordx2 v[6:7], v[10:11], off offset:2048

;     __device__ __forceinline__ void operator()(int row, int col, const f32x4& acc) const {
;         const f32x4 v = acc * rsqrtf(rowss[row] * (1.0f / 1024.0f) + 1e-6f);
;         if (col < 1024) { u32x2 w; w.x = cvt_pk_bf16(v[0], v[1]); w.y = cvt_pk_bf16(v[2], v[3]); *(u32x2*)(U + (size_t)row * DM + col) = w; }
;         else { u32x2 w; w.x = cvt_pk_bf16(silu_f(v[0]), silu_f(v[1])); w.y = cvt_pk_bf16(silu_f(v[2]), silu_f(v[3])); *(u32x2*)(SG + (size_t)row * DM + col - 1024) = w; } }
; template <int KS, class Epi>
; __device__ __forceinline__ void small_gemm(const bf16_t* __restrict__ A, int lda, int a_grp_step, const bf16_t* __restrict__ Bt, int N, const Epi& E, LAS unsigned char* lds) {
;     ...
;     for (int pair = blockIdx.x; pair * 2 < ntile; pair += gridDim.x) {
;         const int tile = pair * 2 + th, tr = tile & 15, tc = tile >> 4, row0 = MP + tr * 32, col0 = tc * 32;
;         const bf16_t* ap = A + (size_t)(row0 + fr) * lda + (col0 >> 8) * a_grp_step + kq * (KS * 32) + 8 * fq;
;         const bf16_t* bp = Bt + (size_t)(col0 + fr) * K + kq * (KS * 32) + 8 * fq;
;         bf16x8 a[KS][2], b[KS][2];
; #pragma unroll
;         for (int k = 0; k < KS; ++k)
; #pragma unroll
;             for (int m = 0; m < 2; ++m) { a[k][m] = *(const bf16x8*)(ap + (size_t)(16 * m) * lda + 32 * k); b[k][m] = *(const bf16x8*)(bp + (size_t)(16 * m) * K + 32 * k); }
;         f32x4 acc[2][2];
; #pragma unroll
;         for (int mi = 0; mi < 2; ++mi)
; #pragma unroll
;             for (int ni = 0; ni < 2; ++ni) acc[mi][ni] = (f32x4){0.f, 0.f, 0.f, 0.f};
; #pragma unroll
;         for (int k = 0; k < KS; ++k)
; #pragma unroll
;             for (int mi = 0; mi < 2; ++mi)
; #pragma unroll
;                 for (int ni = 0; ni < 2; ++ni) acc[mi][ni] = mfma16(b[k][ni], a[k][mi], acc[mi][ni]);
; #pragma unroll
;         for (int mi = 0; mi < 2; ++mi)
; #pragma unroll
;             for (int ni = 0; ni < 2; ++ni) red[(wid * 4 + mi * 2 + ni) * 64 + lane] = acc[mi][ni];
;         lds_barrier();
;         {
;             const int sub = kq, mi = sub >> 1, ni = sub & 1;
;             f32x4 s = red[((th * 4 + 0) * 4 + sub) * 64 + lane];
; #pragma unroll
;             for (int q = 1; q < 4; ++q) s += red[((th * 4 + q) * 4 + sub) * 64 + lane];
;             E(row0 + 16 * mi + fr, col0 + 16 * ni + 4 * fq, s);
.LBB0_934:
	v_and_b32_e32 v67, 0xffffffe0, v17
	v_or_b32_e32 v6, v67, v157
	v_and_b32_e32 v0, 0x1e0, v18
	v_ashrrev_i32_e32 v7, 31, v6
	v_or_b32_e32 v66, 0x4000, v0
	v_lshlrev_b64 v[6:7], 11, v[6:7]
	v_lshl_add_u64 v[58:59], v[4:5], 0, v[6:7]
	v_or_b32_e32 v0, v66, v157
	v_lshlrev_b32_e32 v0, 11, v0
	v_lshl_add_u64 v[60:61], v[2:3], 0, v[0:1]
	v_add_co_u32_e32 v62, vcc, s8, v60
	v_addc_co_u32_e32 v63, vcc, 0, v61, vcc
	v_add_co_u32_e32 v64, vcc, s8, v58
	v_addc_co_u32_e32 v65, vcc, 0, v59, vcc
	v_or_b32_e32 v0, v15, v66
	v_lshl_add_u64 v[144:145], v[0:1], 2, s[14:15]
	global_load_dword v140, v[144:145], off
	global_load_dwordx4 v[158:161], v[58:59], off
	global_load_dwordx4 v[162:165], v[60:61], off
	global_load_dwordx4 v[166:169], v[62:63], off
	global_load_dwordx4 v[170:173], v[64:65], off
	global_load_dwordx4 v[174:177], v[58:59], off offset:64
	global_load_dwordx4 v[178:181], v[60:61], off offset:64
	global_load_dwordx4 v[186:189], v[62:63], off offset:64
	global_load_dwordx4 v[190:193], v[64:65], off offset:64
	global_load_dwordx4 v[194:197], v[58:59], off offset:128
	global_load_dwordx4 v[198:201], v[60:61], off offset:128
	global_load_dwordx4 v[202:205], v[62:63], off offset:128
	global_load_dwordx4 v[206:209], v[64:65], off offset:128
	global_load_dwordx4 v[210:213], v[58:59], off offset:192
	global_load_dwordx4 v[214:217], v[60:61], off offset:192
	global_load_dwordx4 v[218:221], v[62:63], off offset:192
	global_load_dwordx4 v[222:225], v[64:65], off offset:192
	global_load_dwordx4 v[226:229], v[58:59], off offset:256
	global_load_dwordx4 v[230:233], v[60:61], off offset:256
	global_load_dwordx4 v[234:237], v[62:63], off offset:256
	global_load_dwordx4 v[238:241], v[64:65], off offset:256
	global_load_dwordx4 v[242:245], v[58:59], off offset:320
	global_load_dwordx4 v[118:121], v[60:61], off offset:320
	global_load_dwordx4 v[122:125], v[62:63], off offset:320
	global_load_dwordx4 v[148:151], v[64:65], off offset:320
	s_waitcnt vmcnt(20)
	v_mfma_f32_16x16x32_bf16 v[6:9], v[158:161], v[162:165], 0
	v_mfma_f32_16x16x32_bf16 v[10:13], v[158:161], v[166:169], 0
	v_mfma_f32_16x16x32_bf16 v[22:25], v[170:173], v[162:165], 0
	v_mfma_f32_16x16x32_bf16 v[26:29], v[170:173], v[166:169], 0
	global_load_dwordx4 v[158:161], v[58:59], off offset:384
	global_load_dwordx4 v[162:165], v[60:61], off offset:384
	global_load_dwordx4 v[166:169], v[62:63], off offset:384
	global_load_dwordx4 v[170:173], v[64:65], off offset:384
	s_waitcnt vmcnt(20)
	v_mfma_f32_16x16x32_bf16 v[6:9], v[174:177], v[178:181], v[6:9]
	v_mfma_f32_16x16x32_bf16 v[10:13], v[174:177], v[186:189], v[10:13]
	v_mfma_f32_16x16x32_bf16 v[22:25], v[190:193], v[178:181], v[22:25]
	v_mfma_f32_16x16x32_bf16 v[26:29], v[190:193], v[186:189], v[26:29]
	global_load_dwordx4 v[174:177], v[58:59], off offset:448
	global_load_dwordx4 v[178:181], v[60:61], off offset:448
	global_load_dwordx4 v[186:189], v[62:63], off offset:448
	global_load_dwordx4 v[190:193], v[64:65], off offset:448
	s_waitcnt vmcnt(20)
	v_mfma_f32_16x16x32_bf16 v[6:9], v[194:197], v[198:201], v[6:9]
	v_mfma_f32_16x16x32_bf16 v[10:13], v[194:197], v[202:205], v[10:13]
	v_mfma_f32_16x16x32_bf16 v[22:25], v[206:209], v[198:201], v[22:25]
	v_mfma_f32_16x16x32_bf16 v[26:29], v[206:209], v[202:205], v[26:29]
	s_waitcnt vmcnt(16)
	v_mfma_f32_16x16x32_bf16 v[6:9], v[210:213], v[214:217], v[6:9]
	v_mfma_f32_16x16x32_bf16 v[10:13], v[210:213], v[218:221], v[10:13]
	v_mfma_f32_16x16x32_bf16 v[22:25], v[222:225], v[214:217], v[22:25]
	v_mfma_f32_16x16x32_bf16 v[26:29], v[222:225], v[218:221], v[26:29]
	s_waitcnt vmcnt(12)
	v_mfma_f32_16x16x32_bf16 v[6:9], v[226:229], v[230:233], v[6:9]
	v_mfma_f32_16x16x32_bf16 v[10:13], v[226:229], v[234:237], v[10:13]
	v_mfma_f32_16x16x32_bf16 v[22:25], v[238:241], v[230:233], v[22:25]
	v_mfma_f32_16x16x32_bf16 v[26:29], v[238:241], v[234:237], v[26:29]
	s_waitcnt vmcnt(8)
	v_mfma_f32_16x16x32_bf16 v[6:9], v[242:245], v[118:121], v[6:9]
	v_mfma_f32_16x16x32_bf16 v[10:13], v[242:245], v[122:125], v[10:13]
	v_mfma_f32_16x16x32_bf16 v[22:25], v[148:151], v[118:121], v[22:25]
	v_mfma_f32_16x16x32_bf16 v[26:29], v[148:151], v[122:125], v[26:29]
	s_waitcnt vmcnt(4)
	v_mfma_f32_16x16x32_bf16 v[6:9], v[158:161], v[162:165], v[6:9]
	v_mfma_f32_16x16x32_bf16 v[10:13], v[158:161], v[166:169], v[10:13]
	v_mfma_f32_16x16x32_bf16 v[22:25], v[170:173], v[162:165], v[22:25]
	v_mfma_f32_16x16x32_bf16 v[26:29], v[170:173], v[166:169], v[26:29]
	s_waitcnt vmcnt(0)
	v_mfma_f32_16x16x32_bf16 v[6:9], v[174:177], v[178:181], v[6:9]
	v_mfma_f32_16x16x32_bf16 v[10:13], v[174:177], v[186:189], v[10:13]
	v_mfma_f32_16x16x32_bf16 v[22:25], v[190:193], v[178:181], v[22:25]
	v_mfma_f32_16x16x32_bf16 v[26:29], v[190:193], v[186:189], v[26:29]
	s_nop 7
	s_nop 3
	ds_write_b128 v19, v[6:9]
	ds_write_b128 v19, v[22:25] offset:1024
	ds_write_b128 v19, v[10:13] offset:2048
	ds_write_b128 v19, v[26:29] offset:3072
	s_waitcnt lgkmcnt(0)
	s_barrier
	v_lshl_add_u64 v[6:7], v[0:1], 2, s[14:15]
	ds_read_b128 v[8:11], v14
	ds_read_b128 v[22:25], v20 offset:4096
	ds_read_b128 v[26:29], v20 offset:8192
	ds_read_b128 v[30:33], v20 offset:12288
	v_or_b32_e32 v6, v67, v16
	v_cmp_lt_i32_e32 vcc, s12, v6
	s_waitcnt lgkmcnt(2)
	v_pk_add_f32 v[10:11], v[10:11], v[24:25]
	v_pk_add_f32 v[8:9], v[8:9], v[22:23]
	s_waitcnt lgkmcnt(1)
	v_pk_add_f32 v[10:11], v[10:11], v[28:29]
	v_pk_add_f32 v[8:9], v[8:9], v[26:27]
	s_waitcnt lgkmcnt(0)
	v_pk_add_f32 v[10:11], v[10:11], v[32:33]
	v_pk_add_f32 v[8:9], v[8:9], v[30:31]
	s_waitcnt vmcnt(0)
	v_fmamk_f32 v7, v140, 0x3a800000, v21
	v_mul_f32_e32 v12, 0x4b800000, v7
	v_cmp_gt_f32_e64 s[2:3], s9, v7
	s_nop 1
	v_cndmask_b32_e64 v7, v7, v12, s[2:3]
	v_rsq_f32_e32 v7, v7
	s_nop 0
	v_mul_f32_e32 v12, 0x45800000, v7
	v_cndmask_b32_e64 v12, v7, v12, s[2:3]
	v_pk_mul_f32 v[10:11], v[10:11], v[12:13] op_sel_hi:[1,0]
	v_pk_mul_f32 v[12:13], v[8:9], v[12:13] op_sel_hi:[1,0]
	v_lshlrev_b64 v[8:9], 11, v[0:1]
	s_and_saveexec_b64 s[0:1], vcc
	s_xor_b64 s[0:1], exec, s[0:1]
	s_cbranch_execz .LBB0_936
	v_mul_f32_e32 v0, 0xbfb8aa3b, v12
	v_exp_f32_e32 v0, v0
	v_mul_f32_e32 v7, 0xbfb8aa3b, v13
	v_mul_f32_e32 v23, 0xbfb8aa3b, v11
	v_exp_f32_e32 v7, v7
	v_add_f32_e32 v0, 1.0, v0
	v_rcp_f32_e32 v22, v0
	v_mul_f32_e32 v0, 0xbfb8aa3b, v10
	v_exp_f32_e32 v0, v0
	v_exp_f32_e32 v25, v23
	v_add_f32_e32 v7, 1.0, v7
	v_rcp_f32_e32 v23, v7
	v_add_f32_e32 v0, 1.0, v0
	v_rcp_f32_e32 v24, v0
	v_add_f32_e32 v0, 1.0, v25
	v_rcp_f32_e32 v25, v0
	v_lshl_add_u64 v[8:9], s[50:51], 0, v[8:9]
	v_mov_b32_e32 v7, v1
	v_lshl_add_u64 v[6:7], v[6:7], 1, v[8:9]
	v_pk_mul_f32 v[12:13], v[12:13], v[22:23]
	v_pk_mul_f32 v[10:11], v[10:11], v[24:25]
	v_add_co_u32_e32 v6, vcc, 0x71ff000, v6
	v_cvt_pk_bf16_f32 v12, v12, v13
	v_cvt_pk_bf16_f32 v13, v10, v11
	v_addc_co_u32_e32 v7, vcc, 0, v7, vcc
	global_store_dwordx2 v[6:7], v[12:13], off offset:2048

; __device__ __forceinline__ float bf2f(short b) { return __uint_as_float(((unsigned)(unsigned short)b) << 16); }
;     __device__ __forceinline__ void operator()(int row, int col, const f32x4& acc) const {
;     ...
;         } else { const bf16x4 hb = *(const bf16x4*)(a3 + (size_t)row * DM + col);
;             *(f32x4*)(out + (size_t)row * DM + col) = acc + (f32x4){bf2f(hb[0]), bf2f(hb[1]), bf2f(hb[2]), bf2f(hb[3])}; } }
; template <int KS, class Epi>
; __device__ __forceinline__ void small_gemm(const bf16_t* __restrict__ A, int lda, int a_grp_step, const bf16_t* __restrict__ Bt, int N, const Epi& E, LAS unsigned char* lds) {
;     ...
;     for (int pair = blockIdx.x; pair * 2 < ntile; pair += gridDim.x) {
;         const int tile = pair * 2 + th, tr = tile & 15, tc = tile >> 4, row0 = MP + tr * 32, col0 = tc * 32;
;         const bf16_t* ap = A + (size_t)(row0 + fr) * lda + (col0 >> 8) * a_grp_step + kq * (KS * 32) + 8 * fq;
;         const bf16_t* bp = Bt + (size_t)(col0 + fr) * K + kq * (KS * 32) + 8 * fq;
;         bf16x8 a[KS][2], b[KS][2];
; #pragma unroll
;         for (int k = 0; k < KS; ++k)
; #pragma unroll
;             for (int m = 0; m < 2; ++m) { a[k][m] = *(const bf16x8*)(ap + (size_t)(16 * m) * lda + 32 * k); b[k][m] = *(const bf16x8*)(bp + (size_t)(16 * m) * K + 32 * k); }
;         f32x4 acc[2][2];
; #pragma unroll
;         for (int mi = 0; mi < 2; ++mi)
; #pragma unroll
;             for (int ni = 0; ni < 2; ++ni) acc[mi][ni] = (f32x4){0.f, 0.f, 0.f, 0.f};
; #pragma unroll
;         for (int k = 0; k < KS; ++k)
; #pragma unroll
;             for (int mi = 0; mi < 2; ++mi)
; #pragma unroll
;                 for (int ni = 0; ni < 2; ++ni) acc[mi][ni] = mfma16(b[k][ni], a[k][mi], acc[mi][ni]);
; #pragma unroll
;         for (int mi = 0; mi < 2; ++mi)
; #pragma unroll
;             for (int ni = 0; ni < 2; ++ni) red[(wid * 4 + mi * 2 + ni) * 64 + lane] = acc[mi][ni];
;         lds_barrier();
;         {
;             const int sub = kq, mi = sub >> 1, ni = sub & 1;
;             f32x4 s = red[((th * 4 + 0) * 4 + sub) * 64 + lane];
; #pragma unroll
;             for (int q = 1; q < 4; ++q) s += red[((th * 4 + q) * 4 + sub) * 64 + lane];
;             E(row0 + 16 * mi + fr, col0 + 16 * ni + 4 * fq, s);
.LBB0_1459:
	v_and_b32_e32 v0, 0x1e0, v11
	v_and_b32_e32 v66, 0xffffffe0, v10
	v_or_b32_e32 v67, 0x4000, v0
	v_or_b32_e32 v14, v66, v146
	v_or_b32_e32 v0, v67, v146
	v_ashrrev_i32_e32 v15, 31, v14
	v_lshlrev_b32_e32 v0, 11, v0
	v_lshlrev_b64 v[14:15], 11, v[14:15]
	v_lshl_add_u64 v[58:59], v[2:3], 0, v[0:1]
	v_lshl_add_u64 v[60:61], v[4:5], 0, v[14:15]
	v_add_co_u32_e32 v62, vcc, s6, v58
	v_addc_co_u32_e32 v63, vcc, 0, v59, vcc
	v_add_co_u32_e32 v64, vcc, s6, v60
	s_add_i32 s7, s7, s86
	v_addc_co_u32_e32 v65, vcc, 0, v61, vcc
	v_add_u32_e32 v10, s4, v10
	s_cmpk_lt_i32 s7, 0x100
	v_add_u32_e32 v11, s5, v11
	v_or_b32_e32 v38, v67, v9
	v_lshlrev_b32_e32 v0, 11, v38
	v_or_b32_e32 v34, v66, v8
	v_ashrrev_i32_e32 v35, 31, v34
	v_lshl_add_u64 v[36:37], s[0:1], 0, v[0:1]
	v_lshl_add_u64 v[36:37], v[34:35], 1, v[36:37]
	v_lshlrev_b32_e32 v0, 12, v38
	global_load_dwordx2 v[140:141], v[36:37], off
	global_load_dwordx4 v[158:161], v[60:61], off
	global_load_dwordx4 v[162:165], v[58:59], off
	global_load_dwordx4 v[166:169], v[62:63], off
	global_load_dwordx4 v[170:173], v[64:65], off
	global_load_dwordx4 v[174:177], v[60:61], off offset:64
	global_load_dwordx4 v[178:181], v[58:59], off offset:64
	global_load_dwordx4 v[186:189], v[62:63], off offset:64
	global_load_dwordx4 v[190:193], v[64:65], off offset:64
	global_load_dwordx4 v[194:197], v[60:61], off offset:128
	global_load_dwordx4 v[198:201], v[58:59], off offset:128
	global_load_dwordx4 v[202:205], v[62:63], off offset:128
	global_load_dwordx4 v[206:209], v[64:65], off offset:128
	global_load_dwordx4 v[210:213], v[60:61], off offset:192
	global_load_dwordx4 v[214:217], v[58:59], off offset:192
	global_load_dwordx4 v[218:221], v[62:63], off offset:192
	global_load_dwordx4 v[222:225], v[64:65], off offset:192
	global_load_dwordx4 v[226:229], v[60:61], off offset:256
	global_load_dwordx4 v[230:233], v[58:59], off offset:256
	global_load_dwordx4 v[234:237], v[62:63], off offset:256
	global_load_dwordx4 v[238:241], v[64:65], off offset:256
	global_load_dwordx4 v[242:245], v[60:61], off offset:320
	global_load_dwordx4 v[118:121], v[58:59], off offset:320
	global_load_dwordx4 v[122:125], v[62:63], off offset:320
	global_load_dwordx4 v[148:151], v[64:65], off offset:320
	s_waitcnt vmcnt(20)
	v_mfma_f32_16x16x32_bf16 v[14:17], v[158:161], v[162:165], 0
	v_mfma_f32_16x16x32_bf16 v[18:21], v[158:161], v[166:169], 0
	v_mfma_f32_16x16x32_bf16 v[22:25], v[170:173], v[162:165], 0
	v_mfma_f32_16x16x32_bf16 v[26:29], v[170:173], v[166:169], 0
	global_load_dwordx4 v[158:161], v[60:61], off offset:384
	global_load_dwordx4 v[162:165], v[58:59], off offset:384
	global_load_dwordx4 v[166:169], v[62:63], off offset:384
	global_load_dwordx4 v[170:173], v[64:65], off offset:384
	s_waitcnt vmcnt(20)
	v_mfma_f32_16x16x32_bf16 v[14:17], v[174:177], v[178:181], v[14:17]
	v_mfma_f32_16x16x32_bf16 v[18:21], v[174:177], v[186:189], v[18:21]
	v_mfma_f32_16x16x32_bf16 v[22:25], v[190:193], v[178:181], v[22:25]
	v_mfma_f32_16x16x32_bf16 v[26:29], v[190:193], v[186:189], v[26:29]
	global_load_dwordx4 v[174:177], v[60:61], off offset:448
	global_load_dwordx4 v[178:181], v[58:59], off offset:448
	global_load_dwordx4 v[186:189], v[62:63], off offset:448
	global_load_dwordx4 v[190:193], v[64:65], off offset:448
	s_waitcnt vmcnt(20)
	v_mfma_f32_16x16x32_bf16 v[14:17], v[194:197], v[198:201], v[14:17]
	v_mfma_f32_16x16x32_bf16 v[18:21], v[194:197], v[202:205], v[18:21]
	v_mfma_f32_16x16x32_bf16 v[22:25], v[206:209], v[198:201], v[22:25]
	v_mfma_f32_16x16x32_bf16 v[26:29], v[206:209], v[202:205], v[26:29]
	s_waitcnt vmcnt(16)
	v_mfma_f32_16x16x32_bf16 v[14:17], v[210:213], v[214:217], v[14:17]
	v_mfma_f32_16x16x32_bf16 v[18:21], v[210:213], v[218:221], v[18:21]
	v_mfma_f32_16x16x32_bf16 v[22:25], v[222:225], v[214:217], v[22:25]
	v_mfma_f32_16x16x32_bf16 v[26:29], v[222:225], v[218:221], v[26:29]
	s_waitcnt vmcnt(12)
	v_mfma_f32_16x16x32_bf16 v[14:17], v[226:229], v[230:233], v[14:17]
	v_mfma_f32_16x16x32_bf16 v[18:21], v[226:229], v[234:237], v[18:21]
	v_mfma_f32_16x16x32_bf16 v[22:25], v[238:241], v[230:233], v[22:25]
	v_mfma_f32_16x16x32_bf16 v[26:29], v[238:241], v[234:237], v[26:29]
	s_waitcnt vmcnt(8)
	v_mfma_f32_16x16x32_bf16 v[14:17], v[242:245], v[118:121], v[14:17]
	v_mfma_f32_16x16x32_bf16 v[18:21], v[242:245], v[122:125], v[18:21]
	v_mfma_f32_16x16x32_bf16 v[22:25], v[148:151], v[118:121], v[22:25]
	v_mfma_f32_16x16x32_bf16 v[26:29], v[148:151], v[122:125], v[26:29]
	s_waitcnt vmcnt(4)
	v_mfma_f32_16x16x32_bf16 v[14:17], v[158:161], v[162:165], v[14:17]
	v_mfma_f32_16x16x32_bf16 v[18:21], v[158:161], v[166:169], v[18:21]
	v_mfma_f32_16x16x32_bf16 v[22:25], v[170:173], v[162:165], v[22:25]
	v_mfma_f32_16x16x32_bf16 v[26:29], v[170:173], v[166:169], v[26:29]
	s_waitcnt vmcnt(0)
	v_mfma_f32_16x16x32_bf16 v[14:17], v[174:177], v[178:181], v[14:17]
	v_mfma_f32_16x16x32_bf16 v[18:21], v[174:177], v[186:189], v[18:21]
	v_mfma_f32_16x16x32_bf16 v[22:25], v[190:193], v[178:181], v[22:25]
	v_mfma_f32_16x16x32_bf16 v[26:29], v[190:193], v[186:189], v[26:29]
	s_nop 7
	s_nop 3
	ds_write_b128 v12, v[14:17]
	ds_write_b128 v12, v[22:25] offset:1024
	ds_write_b128 v12, v[18:21] offset:2048
	ds_write_b128 v12, v[26:29] offset:3072
	s_waitcnt lgkmcnt(0)
	s_barrier
	v_lshl_add_u64 v[14:15], s[48:49], 0, v[0:1]
	v_lshl_add_u64 v[32:33], v[34:35], 2, v[14:15]
	ds_read_b128 v[14:17], v7
	ds_read_b128 v[18:21], v13 offset:4096
	ds_read_b128 v[22:25], v13 offset:8192
	ds_read_b128 v[26:29], v13 offset:12288
	s_waitcnt lgkmcnt(2)
	v_pk_add_f32 v[16:17], v[16:17], v[20:21]
	v_pk_add_f32 v[14:15], v[14:15], v[18:19]
	s_waitcnt lgkmcnt(1)
	v_pk_add_f32 v[16:17], v[16:17], v[24:25]
	v_pk_add_f32 v[14:15], v[14:15], v[22:23]
	s_waitcnt lgkmcnt(0)
	v_pk_add_f32 v[16:17], v[16:17], v[28:29]
	v_pk_add_f32 v[14:15], v[14:15], v[26:27]
	s_waitcnt vmcnt(0)
	v_and_b32_e32 v19, 0xffff0000, v140
	v_lshlrev_b32_e32 v18, 16, v140
	v_and_b32_e32 v21, 0xffff0000, v141
	v_lshlrev_b32_e32 v20, 16, v141
	v_pk_add_f32 v[16:17], v[16:17], v[20:21]
	v_pk_add_f32 v[14:15], v[14:15], v[18:19]
	global_store_dwordx4 v[32:33], v[14:17], off
	s_waitcnt lgkmcnt(0)
	s_barrier
	s_cbranch_scc1 .LBB0_1459

; __device__ __forceinline__ float bf2f(short b) { return __uint_as_float(((unsigned)(unsigned short)b) << 16); }
;     __device__ __forceinline__ void operator()(int row, int col, const f32x4& acc) const {
;     ...
;         } else { const bf16x4 hb = *(const bf16x4*)(a3 + (size_t)row * DM + col);
;             *(f32x4*)(out + (size_t)row * DM + col) = acc + (f32x4){bf2f(hb[0]), bf2f(hb[1]), bf2f(hb[2]), bf2f(hb[3])}; } }
; template <int KS, class Epi>
; __device__ __forceinline__ void small_gemm(const bf16_t* __restrict__ A, int lda, int a_grp_step, const bf16_t* __restrict__ Bt, int N, const Epi& E, LAS unsigned char* lds) {
;     ...
;     for (int pair = blockIdx.x; pair * 2 < ntile; pair += gridDim.x) {
;         const int tile = pair * 2 + th, tr = tile & 15, tc = tile >> 4, row0 = MP + tr * 32, col0 = tc * 32;
;         const bf16_t* ap = A + (size_t)(row0 + fr) * lda + (col0 >> 8) * a_grp_step + kq * (KS * 32) + 8 * fq;
;         const bf16_t* bp = Bt + (size_t)(col0 + fr) * K + kq * (KS * 32) + 8 * fq;
;         bf16x8 a[KS][2], b[KS][2];
; #pragma unroll
;         for (int k = 0; k < KS; ++k)
; #pragma unroll
;             for (int m = 0; m < 2; ++m) { a[k][m] = *(const bf16x8*)(ap + (size_t)(16 * m) * lda + 32 * k); b[k][m] = *(const bf16x8*)(bp + (size_t)(16 * m) * K + 32 * k); }
;         f32x4 acc[2][2];
; #pragma unroll
;         for (int mi = 0; mi < 2; ++mi)
; #pragma unroll
;             for (int ni = 0; ni < 2; ++ni) acc[mi][ni] = (f32x4){0.f, 0.f, 0.f, 0.f};
; #pragma unroll
;         for (int k = 0; k < KS; ++k)
; #pragma unroll
;             for (int mi = 0; mi < 2; ++mi)
; #pragma unroll
;                 for (int ni = 0; ni < 2; ++ni) acc[mi][ni] = mfma16(b[k][ni], a[k][mi], acc[mi][ni]);
; #pragma unroll
;         for (int mi = 0; mi < 2; ++mi)
; #pragma unroll
;             for (int ni = 0; ni < 2; ++ni) red[(wid * 4 + mi * 2 + ni) * 64 + lane] = acc[mi][ni];
;         lds_barrier();
;         {
;             const int sub = kq, mi = sub >> 1, ni = sub & 1;
;             f32x4 s = red[((th * 4 + 0) * 4 + sub) * 64 + lane];
; #pragma unroll
;             for (int q = 1; q < 4; ++q) s += red[((th * 4 + q) * 4 + sub) * 64 + lane];
;             E(row0 + 16 * mi + fr, col0 + 16 * ni + 4 * fq, s);
.LBB0_1486:
	v_and_b32_e32 v0, 0x1e0, v10
	v_and_b32_e32 v13, 0xffffffe0, v9
	v_or_b32_e32 v66, 0x4000, v0
	v_or_b32_e32 v14, v13, v146
	v_or_b32_e32 v0, v66, v146
	v_ashrrev_i32_e32 v15, 31, v14
	v_lshlrev_b32_e32 v0, 11, v0
	v_lshlrev_b64 v[14:15], 11, v[14:15]
	v_lshl_add_u64 v[58:59], v[2:3], 0, v[0:1]
	v_lshl_add_u64 v[60:61], v[4:5], 0, v[14:15]
	v_add_co_u32_e32 v62, vcc, s2, v58
	v_addc_co_u32_e32 v63, vcc, 0, v59, vcc
	v_add_co_u32_e32 v64, vcc, s2, v60
	v_or_b32_e32 v0, v66, v8
	v_addc_co_u32_e32 v65, vcc, 0, v61, vcc
	s_add_i32 s33, s33, s86
	v_add_u32_e32 v9, s0, v9
	s_cmpk_lt_i32 s33, 0x100
	v_add_u32_e32 v10, s1, v10
	v_mov_b32_e32 v35, v1
	v_or_b32_e32 v36, v13, v7
	v_lshlrev_b32_e32 v34, 11, v0
	v_ashrrev_i32_e32 v37, 31, v36
	v_lshl_add_u64 v[34:35], s[4:5], 0, v[34:35]
	v_lshl_add_u64 v[34:35], v[36:37], 1, v[34:35]
	v_lshlrev_b32_e32 v0, 10, v0
	global_load_dwordx2 v[140:141], v[34:35], off
	global_load_dwordx4 v[158:161], v[60:61], off
	global_load_dwordx4 v[162:165], v[58:59], off
	global_load_dwordx4 v[166:169], v[62:63], off
	global_load_dwordx4 v[170:173], v[64:65], off
	global_load_dwordx4 v[174:177], v[60:61], off offset:64
	global_load_dwordx4 v[178:181], v[58:59], off offset:64
	global_load_dwordx4 v[186:189], v[62:63], off offset:64
	global_load_dwordx4 v[190:193], v[64:65], off offset:64
	global_load_dwordx4 v[194:197], v[60:61], off offset:128
	global_load_dwordx4 v[198:201], v[58:59], off offset:128
	global_load_dwordx4 v[202:205], v[62:63], off offset:128
	global_load_dwordx4 v[206:209], v[64:65], off offset:128
	global_load_dwordx4 v[210:213], v[60:61], off offset:192
	global_load_dwordx4 v[214:217], v[58:59], off offset:192
	global_load_dwordx4 v[218:221], v[62:63], off offset:192
	global_load_dwordx4 v[222:225], v[64:65], off offset:192
	global_load_dwordx4 v[226:229], v[60:61], off offset:256
	global_load_dwordx4 v[230:233], v[58:59], off offset:256
	global_load_dwordx4 v[234:237], v[62:63], off offset:256
	global_load_dwordx4 v[238:241], v[64:65], off offset:256
	global_load_dwordx4 v[242:245], v[60:61], off offset:320
	global_load_dwordx4 v[118:121], v[58:59], off offset:320
	global_load_dwordx4 v[122:125], v[62:63], off offset:320
	global_load_dwordx4 v[148:151], v[64:65], off offset:320
	s_waitcnt vmcnt(20)
	v_mfma_f32_16x16x32_bf16 v[14:17], v[158:161], v[162:165], 0
	v_mfma_f32_16x16x32_bf16 v[18:21], v[158:161], v[166:169], 0
	v_mfma_f32_16x16x32_bf16 v[22:25], v[170:173], v[162:165], 0
	v_mfma_f32_16x16x32_bf16 v[26:29], v[170:173], v[166:169], 0
	global_load_dwordx4 v[158:161], v[60:61], off offset:384
	global_load_dwordx4 v[162:165], v[58:59], off offset:384
	global_load_dwordx4 v[166:169], v[62:63], off offset:384
	global_load_dwordx4 v[170:173], v[64:65], off offset:384
	s_waitcnt vmcnt(20)
	v_mfma_f32_16x16x32_bf16 v[14:17], v[174:177], v[178:181], v[14:17]
	v_mfma_f32_16x16x32_bf16 v[18:21], v[174:177], v[186:189], v[18:21]
	v_mfma_f32_16x16x32_bf16 v[22:25], v[190:193], v[178:181], v[22:25]
	v_mfma_f32_16x16x32_bf16 v[26:29], v[190:193], v[186:189], v[26:29]
	global_load_dwordx4 v[174:177], v[60:61], off offset:448
	global_load_dwordx4 v[178:181], v[58:59], off offset:448
	global_load_dwordx4 v[186:189], v[62:63], off offset:448
	global_load_dwordx4 v[190:193], v[64:65], off offset:448
	s_waitcnt vmcnt(20)
	v_mfma_f32_16x16x32_bf16 v[14:17], v[194:197], v[198:201], v[14:17]
	v_mfma_f32_16x16x32_bf16 v[18:21], v[194:197], v[202:205], v[18:21]
	v_mfma_f32_16x16x32_bf16 v[22:25], v[206:209], v[198:201], v[22:25]
	v_mfma_f32_16x16x32_bf16 v[26:29], v[206:209], v[202:205], v[26:29]
	s_waitcnt vmcnt(16)
	v_mfma_f32_16x16x32_bf16 v[14:17], v[210:213], v[214:217], v[14:17]
	v_mfma_f32_16x16x32_bf16 v[18:21], v[210:213], v[218:221], v[18:21]
	v_mfma_f32_16x16x32_bf16 v[22:25], v[222:225], v[214:217], v[22:25]
	v_mfma_f32_16x16x32_bf16 v[26:29], v[222:225], v[218:221], v[26:29]
	s_waitcnt vmcnt(12)
	v_mfma_f32_16x16x32_bf16 v[14:17], v[226:229], v[230:233], v[14:17]
	v_mfma_f32_16x16x32_bf16 v[18:21], v[226:229], v[234:237], v[18:21]
	v_mfma_f32_16x16x32_bf16 v[22:25], v[238:241], v[230:233], v[22:25]
	v_mfma_f32_16x16x32_bf16 v[26:29], v[238:241], v[234:237], v[26:29]
	s_waitcnt vmcnt(8)
	v_mfma_f32_16x16x32_bf16 v[14:17], v[242:245], v[118:121], v[14:17]
	v_mfma_f32_16x16x32_bf16 v[18:21], v[242:245], v[122:125], v[18:21]
	v_mfma_f32_16x16x32_bf16 v[22:25], v[148:151], v[118:121], v[22:25]
	v_mfma_f32_16x16x32_bf16 v[26:29], v[148:151], v[122:125], v[26:29]
	s_waitcnt vmcnt(4)
	v_mfma_f32_16x16x32_bf16 v[14:17], v[158:161], v[162:165], v[14:17]
	v_mfma_f32_16x16x32_bf16 v[18:21], v[158:161], v[166:169], v[18:21]
	v_mfma_f32_16x16x32_bf16 v[22:25], v[170:173], v[162:165], v[22:25]
	v_mfma_f32_16x16x32_bf16 v[26:29], v[170:173], v[166:169], v[26:29]
	s_waitcnt vmcnt(0)
	v_mfma_f32_16x16x32_bf16 v[14:17], v[174:177], v[178:181], v[14:17]
	v_mfma_f32_16x16x32_bf16 v[18:21], v[174:177], v[186:189], v[18:21]
	v_mfma_f32_16x16x32_bf16 v[22:25], v[190:193], v[178:181], v[22:25]
	v_mfma_f32_16x16x32_bf16 v[26:29], v[190:193], v[186:189], v[26:29]
	s_nop 7
	s_nop 3
	ds_write_b128 v11, v[14:17]
	ds_write_b128 v11, v[22:25] offset:1024
	ds_write_b128 v11, v[18:21] offset:2048
	ds_write_b128 v11, v[26:29] offset:3072
	s_waitcnt lgkmcnt(0)
	s_barrier
	v_lshl_add_u64 v[14:15], v[0:1], 2, s[48:49]
	v_lshl_add_u64 v[32:33], v[36:37], 2, v[14:15]
	ds_read_b128 v[14:17], v6
	ds_read_b128 v[18:21], v12 offset:4096
	ds_read_b128 v[22:25], v12 offset:8192
	ds_read_b128 v[26:29], v12 offset:12288
	s_waitcnt lgkmcnt(2)
	v_pk_add_f32 v[16:17], v[16:17], v[20:21]
	v_pk_add_f32 v[14:15], v[14:15], v[18:19]
	s_waitcnt lgkmcnt(1)
	v_pk_add_f32 v[16:17], v[16:17], v[24:25]
	v_pk_add_f32 v[14:15], v[14:15], v[22:23]
	s_waitcnt lgkmcnt(0)
	v_pk_add_f32 v[16:17], v[16:17], v[28:29]
	v_pk_add_f32 v[14:15], v[14:15], v[26:27]
	s_waitcnt vmcnt(0)
	v_and_b32_e32 v19, 0xffff0000, v140
	v_lshlrev_b32_e32 v18, 16, v140
	v_and_b32_e32 v21, 0xffff0000, v141
	v_lshlrev_b32_e32 v20, 16, v141
	v_pk_add_f32 v[16:17], v[16:17], v[20:21]
	v_pk_add_f32 v[14:15], v[14:15], v[18:19]
	global_store_dwordx4 v[32:33], v[14:17], off
	s_waitcnt lgkmcnt(0)
	s_barrier
	s_cbranch_scc1 .LBB0_1486
